# v58 + attention: 80 exec-masked, individually waited rel-bias LDS lookups per unit made branch-free (unconditional ds_read_b32 + v_cndmask), 16 reads issued together with one wait
# speedup vs baseline: 1.0028x; 1.0028x over previous
; #define LAS __attribute__((address_space(3)))
; #define MFMA32(a, b, c) __builtin_amdgcn_mfma_f32_32x32x16_bf16((a), (b), (c), 0, 0, 0)
; DEV void attn_compute(const AttnU& a, const bf16x8 (&qf)[4], int tq, bf16_t* OG, float* LSE, LAS unsigned char* lds, int tid) {
;     ...
;     for (int sb = 0; sb < 5; ++sb) {
;         const int sbk = wave + sb, mb = a.mu0 - 64 + 32 * sbk;
;         vb[sb] = (mb >= 0) && (mb < a.Mg);
;         f32x16 acc;
; #pragma unroll
;         for (int i = 0; i < 16; ++i) acc[i] = 0.f;
;         if (vb[sb]) {
;             const LAS unsigned char* kp = lds + AT_K_OFF + (32 * sbk + n) * AT_KP + 16 * hl;
; #pragma unroll
;             for (int ks = 0; ks < 4; ++ks) { const bf16x8 kf = *(const LAS bf16x8*)(kp + 32 * ks); acc = MFMA32(kf, qf[ks], acc); }
;         }
; #pragma unroll
;         for (int rg = 0; rg < 16; ++rg) {
;             const int jj = 32 * sb + (rg & 3) + 8 * (rg >> 2) + 4 * hl - n;
;             const bool ok = vb[sb] && ((unsigned)jj <= 128u);
;             const float bia = tab[ok ? jj : 0];
;             const float v = ok ? acc[rg] * SC + bia : -1e30f;
;             acc[rg] = v; mx = fmaxf(mx, v);
;         }
.LBB0_653:
	s_or_b64 exec, exec, s[6:7]
	s_ashr_i32 s40, s30, 4
	s_mul_i32 s6, s40, 0x204
	v_lshlrev_b32_e32 v21, 2, v47
	s_add_i32 s6, s6, 0
	v_sub_u32_e32 v71, v21, v147
	s_movk_i32 s7, 0x81
	s_add_i32 s6, s6, 0x19a00
	v_cmp_gt_u32_e32 vcc, s7, v71
	s_and_b64 vcc, s[2:3], vcc
	v_lshl_add_u32 v53, v71, 2, s6
	v_mov_b32_e32 v170, 0xf149f2ca
	ds_read_b32 v48, v53 offset:4
	ds_read_b32 v51, v53 offset:8
	ds_read_b32 v50, v53 offset:12
	ds_read_b32 v70, v53 offset:32
	ds_read_b32 v52, v53 offset:36
	ds_read_b32 v73, v53 offset:40
	ds_read_b32 v72, v53 offset:44
	ds_read_b32 v75, v53 offset:64
	ds_read_b32 v74, v53 offset:68
	ds_read_b32 v77, v53 offset:72
	ds_read_b32 v76, v53 offset:76
	ds_read_b32 v80, v53 offset:96
	ds_read_b32 v79, v53 offset:100
	ds_read_b32 v82, v53 offset:104
	ds_read_b32 v81, v53 offset:108
	ds_read_b32 v49, v53
	s_waitcnt lgkmcnt(0)
	v_fmac_f32_e32 v49, 0x3e38aa3b, v0
	v_cndmask_b32_e32 v49, v170, v49, vcc
.LBB0_655:
	v_add_u32_e32 v0, 1, v71
	s_movk_i32 s6, 0x81
	v_cmp_gt_u32_e32 vcc, s6, v0
	s_and_b64 vcc, s[2:3], vcc
	v_fmac_f32_e32 v48, 0x3e38aa3b, v1
	v_cndmask_b32_e32 v48, v170, v48, vcc
.LBB0_657:
	v_add_u32_e32 v0, 2, v71
	s_movk_i32 s6, 0x81
	v_cmp_gt_u32_e32 vcc, s6, v0
	s_and_b64 vcc, s[2:3], vcc
	v_fmac_f32_e32 v51, 0x3e38aa3b, v2
	v_cndmask_b32_e32 v51, v170, v51, vcc
.LBB0_659:
	v_add_u32_e32 v0, 3, v71
	s_movk_i32 s6, 0x81
	v_cmp_gt_u32_e32 vcc, s6, v0
	s_and_b64 vcc, s[2:3], vcc
	v_fmac_f32_e32 v50, 0x3e38aa3b, v3
	v_cndmask_b32_e32 v50, v170, v50, vcc
.LBB0_661:
	v_add_u32_e32 v0, 8, v71
	s_movk_i32 s6, 0x81
	v_cmp_gt_u32_e32 vcc, s6, v0
	s_and_b64 vcc, s[2:3], vcc
	v_fmac_f32_e32 v70, 0x3e38aa3b, v4
	v_cndmask_b32_e32 v70, v170, v70, vcc
.LBB0_663:
	v_add_u32_e32 v0, 9, v71
	s_movk_i32 s6, 0x81
	v_cmp_gt_u32_e32 vcc, s6, v0
	s_and_b64 vcc, s[2:3], vcc
	v_fmac_f32_e32 v52, 0x3e38aa3b, v5
	v_cndmask_b32_e32 v52, v170, v52, vcc
.LBB0_665:
	v_add_u32_e32 v0, 10, v71
	s_movk_i32 s6, 0x81
	v_cmp_gt_u32_e32 vcc, s6, v0
	s_and_b64 vcc, s[2:3], vcc
	v_fmac_f32_e32 v73, 0x3e38aa3b, v6
	v_cndmask_b32_e32 v73, v170, v73, vcc
.LBB0_667:
	v_add_u32_e32 v0, 11, v71
	s_movk_i32 s6, 0x81
	v_cmp_gt_u32_e32 vcc, s6, v0
	s_and_b64 vcc, s[2:3], vcc
	v_fmac_f32_e32 v72, 0x3e38aa3b, v7
	v_cndmask_b32_e32 v72, v170, v72, vcc
.LBB0_669:
	v_add_u32_e32 v0, 16, v71
	s_movk_i32 s6, 0x81
	v_cmp_gt_u32_e32 vcc, s6, v0
	s_and_b64 vcc, s[2:3], vcc
	v_fmac_f32_e32 v75, 0x3e38aa3b, v8
	v_cndmask_b32_e32 v75, v170, v75, vcc
.LBB0_671:
	v_add_u32_e32 v0, 17, v71
	s_movk_i32 s6, 0x81
	v_cmp_gt_u32_e32 vcc, s6, v0
	s_and_b64 vcc, s[2:3], vcc
	v_fmac_f32_e32 v74, 0x3e38aa3b, v9
	v_cndmask_b32_e32 v74, v170, v74, vcc
.LBB0_673:
	v_add_u32_e32 v0, 18, v71
	s_movk_i32 s6, 0x81
	v_cmp_gt_u32_e32 vcc, s6, v0
	s_and_b64 vcc, s[2:3], vcc
	v_fmac_f32_e32 v77, 0x3e38aa3b, v10
	v_cndmask_b32_e32 v77, v170, v77, vcc
.LBB0_675:
	v_add_u32_e32 v0, 19, v71
	s_movk_i32 s6, 0x81
	v_cmp_gt_u32_e32 vcc, s6, v0
	s_and_b64 vcc, s[2:3], vcc
	v_fmac_f32_e32 v76, 0x3e38aa3b, v11
	v_cndmask_b32_e32 v76, v170, v76, vcc
.LBB0_677:
	v_add_u32_e32 v0, 24, v71
	s_movk_i32 s6, 0x81
	v_cmp_gt_u32_e32 vcc, s6, v0
	s_and_b64 vcc, s[2:3], vcc
	v_fmac_f32_e32 v80, 0x3e38aa3b, v12
	v_cndmask_b32_e32 v80, v170, v80, vcc
.LBB0_679:
	v_add_u32_e32 v0, 25, v71
	s_movk_i32 s6, 0x81
	v_cmp_gt_u32_e32 vcc, s6, v0
	s_and_b64 vcc, s[2:3], vcc
	v_fmac_f32_e32 v79, 0x3e38aa3b, v13
	v_cndmask_b32_e32 v79, v170, v79, vcc
.LBB0_681:
	v_add_u32_e32 v0, 26, v71
	s_movk_i32 s6, 0x81
	v_cmp_gt_u32_e32 vcc, s6, v0
	s_and_b64 vcc, s[2:3], vcc
	v_fmac_f32_e32 v82, 0x3e38aa3b, v14
	v_cndmask_b32_e32 v82, v170, v82, vcc
.LBB0_683:
	v_add_u32_e32 v0, 27, v71
	s_movk_i32 s6, 0x81
	v_cmp_gt_u32_e32 vcc, s6, v0
	s_and_b64 vcc, s[2:3], vcc
	v_fmac_f32_e32 v81, 0x3e38aa3b, v15
	v_cndmask_b32_e32 v81, v170, v81, vcc
.LBB0_685:
	v_add_u32_e32 v149, 1, v78
	v_lshlrev_b32_e32 v83, 5, v149
	v_add_u32_e32 v0, s42, v83
	v_cmp_lt_i32_e32 vcc, -1, v0
	v_cmp_gt_i32_e64 s[36:37], s29, v0
	s_and_b64 s[6:7], vcc, s[36:37]
	v_mov_b32_e32 v0, 0
	v_mov_b32_e32 v1, 0
	v_mov_b32_e32 v2, 0
	v_mov_b32_e32 v3, 0
	v_mov_b32_e32 v4, 0
	v_mov_b32_e32 v5, 0
	v_mov_b32_e32 v6, 0
	v_mov_b32_e32 v7, 0
	v_mov_b32_e32 v8, 0
	v_mov_b32_e32 v9, 0
	v_mov_b32_e32 v10, 0
	v_mov_b32_e32 v11, 0
	v_mov_b32_e32 v12, 0
	v_mov_b32_e32 v13, 0
	v_mov_b32_e32 v14, 0
	v_mov_b32_e32 v15, 0
	s_and_saveexec_b64 s[30:31], s[6:7]
	s_cbranch_execz .LBB0_687
	v_or_b32_e32 v0, v83, v147
	v_mad_u64_u32 v[88:89], s[34:35], v0, s48, v[46:47]
	ds_read_b128 v[0:3], v88
	ds_read_b128 v[84:87], v88 offset:32
	s_waitcnt lgkmcnt(1)
	v_mfma_f32_32x32x16_bf16 v[0:15], v[0:3], v[66:69], 0
	s_waitcnt lgkmcnt(0)
	v_mfma_f32_32x32x16_bf16 v[0:15], v[84:87], v[62:65], v[0:15]
	ds_read_b128 v[84:87], v88 offset:64
	s_waitcnt lgkmcnt(0)
	v_mfma_f32_32x32x16_bf16 v[0:15], v[84:87], v[58:61], v[0:15]
	ds_read_b128 v[84:87], v88 offset:96
	s_waitcnt lgkmcnt(0)
	v_mfma_f32_32x32x16_bf16 v[0:15], v[84:87], v[54:57], v[0:15]
.LBB0_687:
	s_or_b64 exec, exec, s[30:31]
	ds_read_b32 v83, v53 offset:132
	ds_read_b32 v86, v53 offset:136
	ds_read_b32 v85, v53 offset:140
	ds_read_b32 v88, v53 offset:160
	ds_read_b32 v87, v53 offset:164
	ds_read_b32 v90, v53 offset:168
	ds_read_b32 v89, v53 offset:172
	ds_read_b32 v92, v53 offset:192
	ds_read_b32 v91, v53 offset:196
	ds_read_b32 v94, v53 offset:200
	ds_read_b32 v93, v53 offset:204
	ds_read_b32 v96, v53 offset:224
	ds_read_b32 v95, v53 offset:228
	ds_read_b32 v98, v53 offset:232
	ds_read_b32 v97, v53 offset:236
	ds_read_b32 v84, v53 offset:128
	s_waitcnt lgkmcnt(0)
	s_nop 4
	v_fmac_f32_e32 v84, 0x3e38aa3b, v0
	s_mov_b64 vcc, s[6:7]
	v_cndmask_b32_e32 v84, v170, v84, vcc
; #define LAS __attribute__((address_space(3)))
; #define MFMA32(a, b, c) __builtin_amdgcn_mfma_f32_32x32x16_bf16((a), (b), (c), 0, 0, 0)
; DEV void attn_compute(const AttnU& a, const bf16x8 (&qf)[4], int tq, bf16_t* OG, float* LSE, LAS unsigned char* lds, int tid) {
;     ...
;     for (int sb = 0; sb < 5; ++sb) {
;         const int sbk = wave + sb, mb = a.mu0 - 64 + 32 * sbk;
;         vb[sb] = (mb >= 0) && (mb < a.Mg);
;         f32x16 acc;
; #pragma unroll
;         for (int i = 0; i < 16; ++i) acc[i] = 0.f;
;         if (vb[sb]) {
;             const LAS unsigned char* kp = lds + AT_K_OFF + (32 * sbk + n) * AT_KP + 16 * hl;
; #pragma unroll
;             for (int ks = 0; ks < 4; ++ks) { const bf16x8 kf = *(const LAS bf16x8*)(kp + 32 * ks); acc = MFMA32(kf, qf[ks], acc); }
;         }
; #pragma unroll
;         for (int rg = 0; rg < 16; ++rg) {
;             const int jj = 32 * sb + (rg & 3) + 8 * (rg >> 2) + 4 * hl - n;
;             const bool ok = vb[sb] && ((unsigned)jj <= 128u);
;             const float bia = tab[ok ? jj : 0];
;             const float v = ok ? acc[rg] * SC + bia : -1e30f;
;             acc[rg] = v; mx = fmaxf(mx, v);
;         }
.LBB0_689:
	s_nop 1
	v_fmac_f32_e32 v83, 0x3e38aa3b, v1
	s_mov_b64 vcc, s[6:7]
	v_cndmask_b32_e32 v83, v170, v83, vcc
.LBB0_691:
	v_fmac_f32_e32 v86, 0x3e38aa3b, v2
	s_mov_b64 vcc, s[6:7]
	v_cndmask_b32_e32 v86, v170, v86, vcc
.LBB0_693:
	v_fmac_f32_e32 v85, 0x3e38aa3b, v3
	s_mov_b64 vcc, s[6:7]
	v_cndmask_b32_e32 v85, v170, v85, vcc
.LBB0_695:
	v_fmac_f32_e32 v88, 0x3e38aa3b, v4
	s_mov_b64 vcc, s[6:7]
	v_cndmask_b32_e32 v88, v170, v88, vcc
.LBB0_697:
	v_fmac_f32_e32 v87, 0x3e38aa3b, v5
	s_mov_b64 vcc, s[6:7]
	v_cndmask_b32_e32 v87, v170, v87, vcc
.LBB0_699:
	v_fmac_f32_e32 v90, 0x3e38aa3b, v6
	s_mov_b64 vcc, s[6:7]
	v_cndmask_b32_e32 v90, v170, v90, vcc
.LBB0_701:
	v_fmac_f32_e32 v89, 0x3e38aa3b, v7
	s_mov_b64 vcc, s[6:7]
	v_cndmask_b32_e32 v89, v170, v89, vcc
.LBB0_703:
	v_fmac_f32_e32 v92, 0x3e38aa3b, v8
	s_mov_b64 vcc, s[6:7]
	v_cndmask_b32_e32 v92, v170, v92, vcc
.LBB0_705:
	v_fmac_f32_e32 v91, 0x3e38aa3b, v9
	s_mov_b64 vcc, s[6:7]
	v_cndmask_b32_e32 v91, v170, v91, vcc
.LBB0_707:
	v_fmac_f32_e32 v94, 0x3e38aa3b, v10
	s_mov_b64 vcc, s[6:7]
	v_cndmask_b32_e32 v94, v170, v94, vcc
.LBB0_709:
	v_fmac_f32_e32 v93, 0x3e38aa3b, v11
	s_mov_b64 vcc, s[6:7]
	v_cndmask_b32_e32 v93, v170, v93, vcc
.LBB0_711:
	v_fmac_f32_e32 v96, 0x3e38aa3b, v12
	s_mov_b64 vcc, s[6:7]
	v_cndmask_b32_e32 v96, v170, v96, vcc
.LBB0_713:
	v_fmac_f32_e32 v95, 0x3e38aa3b, v13
	s_mov_b64 vcc, s[6:7]
	v_cndmask_b32_e32 v95, v170, v95, vcc
.LBB0_715:
	v_fmac_f32_e32 v98, 0x3e38aa3b, v14
	s_mov_b64 vcc, s[6:7]
	v_cndmask_b32_e32 v98, v170, v98, vcc
.LBB0_717:
	v_fmac_f32_e32 v97, 0x3e38aa3b, v15
	s_mov_b64 vcc, s[6:7]
	v_cndmask_b32_e32 v97, v170, v97, vcc
.LBB0_719:
	v_add_u32_e32 v150, 2, v78
	v_lshlrev_b32_e32 v99, 5, v150
	v_add_u32_e32 v0, s42, v99
	v_cmp_lt_i32_e32 vcc, -1, v0
	v_cmp_gt_i32_e64 s[36:37], s29, v0
	s_and_b64 s[30:31], vcc, s[36:37]
	v_mov_b32_e32 v0, 0
	v_mov_b32_e32 v1, 0
	v_mov_b32_e32 v2, 0
	v_mov_b32_e32 v3, 0
	v_mov_b32_e32 v4, 0
	v_mov_b32_e32 v5, 0
	v_mov_b32_e32 v6, 0
	v_mov_b32_e32 v7, 0
	v_mov_b32_e32 v8, 0
	v_mov_b32_e32 v9, 0
	v_mov_b32_e32 v10, 0
	v_mov_b32_e32 v11, 0
	v_mov_b32_e32 v12, 0
	v_mov_b32_e32 v13, 0
	v_mov_b32_e32 v14, 0
	v_mov_b32_e32 v15, 0
	s_and_saveexec_b64 s[34:35], s[30:31]
	s_cbranch_execz .LBB0_721
	v_or_b32_e32 v0, v99, v147
	v_mad_u64_u32 v[104:105], s[36:37], v0, s48, v[46:47]
	ds_read_b128 v[0:3], v104
	ds_read_b128 v[100:103], v104 offset:32
	s_waitcnt lgkmcnt(1)
	v_mfma_f32_32x32x16_bf16 v[0:15], v[0:3], v[66:69], 0
	s_waitcnt lgkmcnt(0)
	v_mfma_f32_32x32x16_bf16 v[0:15], v[100:103], v[62:65], v[0:15]
	ds_read_b128 v[100:103], v104 offset:64
	s_waitcnt lgkmcnt(0)
	v_mfma_f32_32x32x16_bf16 v[0:15], v[100:103], v[58:61], v[0:15]
	ds_read_b128 v[100:103], v104 offset:96
	s_waitcnt lgkmcnt(0)
	v_mfma_f32_32x32x16_bf16 v[0:15], v[100:103], v[54:57], v[0:15]
.LBB0_721:
	s_or_b64 exec, exec, s[34:35]
	ds_read_b32 v99, v53 offset:260
	ds_read_b32 v102, v53 offset:264
	ds_read_b32 v101, v53 offset:268
	ds_read_b32 v104, v53 offset:288
	ds_read_b32 v103, v53 offset:292
	ds_read_b32 v106, v53 offset:296
	ds_read_b32 v105, v53 offset:300
	ds_read_b32 v108, v53 offset:320
	ds_read_b32 v107, v53 offset:324
	ds_read_b32 v153, v53 offset:328
	ds_read_b32 v109, v53 offset:332
	ds_read_b32 v155, v53 offset:352
	ds_read_b32 v154, v53 offset:356
	ds_read_b32 v157, v53 offset:360
	ds_read_b32 v156, v53 offset:364
	ds_read_b32 v100, v53 offset:256
	s_waitcnt lgkmcnt(0)
	s_nop 4
	v_fmac_f32_e32 v100, 0x3e38aa3b, v0
	s_mov_b64 vcc, s[30:31]
	v_cndmask_b32_e32 v100, v170, v100, vcc
.LBB0_723:
	s_nop 1
	v_fmac_f32_e32 v99, 0x3e38aa3b, v1
	s_mov_b64 vcc, s[30:31]
	v_cndmask_b32_e32 v99, v170, v99, vcc
.LBB0_725:
	v_fmac_f32_e32 v102, 0x3e38aa3b, v2
	s_mov_b64 vcc, s[30:31]
	v_cndmask_b32_e32 v102, v170, v102, vcc
.LBB0_727:
	v_fmac_f32_e32 v101, 0x3e38aa3b, v3
	s_mov_b64 vcc, s[30:31]
	v_cndmask_b32_e32 v101, v170, v101, vcc
.LBB0_729:
	v_fmac_f32_e32 v104, 0x3e38aa3b, v4
	s_mov_b64 vcc, s[30:31]
	v_cndmask_b32_e32 v104, v170, v104, vcc
.LBB0_731:
	v_fmac_f32_e32 v103, 0x3e38aa3b, v5
	s_mov_b64 vcc, s[30:31]
	v_cndmask_b32_e32 v103, v170, v103, vcc
.LBB0_733:
	v_fmac_f32_e32 v106, 0x3e38aa3b, v6
	s_mov_b64 vcc, s[30:31]
	v_cndmask_b32_e32 v106, v170, v106, vcc
.LBB0_735:
	v_fmac_f32_e32 v105, 0x3e38aa3b, v7
	s_mov_b64 vcc, s[30:31]
	v_cndmask_b32_e32 v105, v170, v105, vcc
.LBB0_737:
	v_fmac_f32_e32 v108, 0x3e38aa3b, v8
	s_mov_b64 vcc, s[30:31]
	v_cndmask_b32_e32 v108, v170, v108, vcc
.LBB0_739:
	v_fmac_f32_e32 v107, 0x3e38aa3b, v9
	s_mov_b64 vcc, s[30:31]
	v_cndmask_b32_e32 v107, v170, v107, vcc
.LBB0_741:
	v_fmac_f32_e32 v153, 0x3e38aa3b, v10
	s_mov_b64 vcc, s[30:31]
	v_cndmask_b32_e32 v153, v170, v153, vcc
.LBB0_743:
	v_fmac_f32_e32 v109, 0x3e38aa3b, v11
	s_mov_b64 vcc, s[30:31]
	v_cndmask_b32_e32 v109, v170, v109, vcc
.LBB0_745:
	v_fmac_f32_e32 v155, 0x3e38aa3b, v12
	s_mov_b64 vcc, s[30:31]
	v_cndmask_b32_e32 v155, v170, v155, vcc
.LBB0_747:
	v_fmac_f32_e32 v154, 0x3e38aa3b, v13
	s_mov_b64 vcc, s[30:31]
	v_cndmask_b32_e32 v154, v170, v154, vcc
.LBB0_749:
	v_fmac_f32_e32 v157, 0x3e38aa3b, v14
	s_mov_b64 vcc, s[30:31]
	v_cndmask_b32_e32 v157, v170, v157, vcc
.LBB0_751:
	v_fmac_f32_e32 v156, 0x3e38aa3b, v15
	s_mov_b64 vcc, s[30:31]
	v_cndmask_b32_e32 v156, v170, v156, vcc
; #define LAS __attribute__((address_space(3)))
; #define MFMA32(a, b, c) __builtin_amdgcn_mfma_f32_32x32x16_bf16((a), (b), (c), 0, 0, 0)
; DEV void attn_compute(const AttnU& a, const bf16x8 (&qf)[4], int tq, bf16_t* OG, float* LSE, LAS unsigned char* lds, int tid) {
;     ...
;     for (int sb = 0; sb < 5; ++sb) {
;         const int sbk = wave + sb, mb = a.mu0 - 64 + 32 * sbk;
;         vb[sb] = (mb >= 0) && (mb < a.Mg);
;         f32x16 acc;
; #pragma unroll
;         for (int i = 0; i < 16; ++i) acc[i] = 0.f;
;         if (vb[sb]) {
;             const LAS unsigned char* kp = lds + AT_K_OFF + (32 * sbk + n) * AT_KP + 16 * hl;
; #pragma unroll
;             for (int ks = 0; ks < 4; ++ks) { const bf16x8 kf = *(const LAS bf16x8*)(kp + 32 * ks); acc = MFMA32(kf, qf[ks], acc); }
;         }
; #pragma unroll
;         for (int rg = 0; rg < 16; ++rg) {
;             const int jj = 32 * sb + (rg & 3) + 8 * (rg >> 2) + 4 * hl - n;
;             const bool ok = vb[sb] && ((unsigned)jj <= 128u);
;             const float bia = tab[ok ? jj : 0];
;             const float v = ok ? acc[rg] * SC + bia : -1e30f;
;             acc[rg] = v; mx = fmaxf(mx, v);
;         }
.LBB0_753:
	v_add_u32_e32 v151, 3, v78
	v_lshlrev_b32_e32 v152, 5, v151
	v_add_u32_e32 v0, s42, v152
	v_cmp_lt_i32_e32 vcc, -1, v0
	v_cmp_gt_i32_e64 s[36:37], s29, v0
	s_and_b64 s[34:35], vcc, s[36:37]
	v_mov_b32_e32 v0, 0
	v_mov_b32_e32 v1, 0
	v_mov_b32_e32 v2, 0
	v_mov_b32_e32 v3, 0
	v_mov_b32_e32 v4, 0
	v_mov_b32_e32 v5, 0
	v_mov_b32_e32 v6, 0
	v_mov_b32_e32 v7, 0
	v_mov_b32_e32 v8, 0
	v_mov_b32_e32 v9, 0
	v_mov_b32_e32 v10, 0
	v_mov_b32_e32 v11, 0
	v_mov_b32_e32 v12, 0
	v_mov_b32_e32 v13, 0
	v_mov_b32_e32 v14, 0
	v_mov_b32_e32 v15, 0
	s_and_saveexec_b64 s[36:37], s[34:35]
	s_cbranch_execz .LBB0_755
	v_or_b32_e32 v0, v152, v147
	v_mad_u64_u32 v[162:163], s[46:47], v0, s48, v[46:47]
	ds_read_b128 v[0:3], v162
	ds_read_b128 v[158:161], v162 offset:32
	s_waitcnt lgkmcnt(1)
	v_mfma_f32_32x32x16_bf16 v[0:15], v[0:3], v[66:69], 0
	s_waitcnt lgkmcnt(0)
	v_mfma_f32_32x32x16_bf16 v[0:15], v[158:161], v[62:65], v[0:15]
	ds_read_b128 v[158:161], v162 offset:64
	s_waitcnt lgkmcnt(0)
	v_mfma_f32_32x32x16_bf16 v[0:15], v[158:161], v[58:61], v[0:15]
	ds_read_b128 v[158:161], v162 offset:96
	s_waitcnt lgkmcnt(0)
	v_mfma_f32_32x32x16_bf16 v[0:15], v[158:161], v[54:57], v[0:15]
.LBB0_755:
	s_or_b64 exec, exec, s[36:37]
	ds_read_b32 v158, v53 offset:388
	ds_read_b32 v161, v53 offset:392
	ds_read_b32 v160, v53 offset:396
	ds_read_b32 v163, v53 offset:416
	ds_read_b32 v162, v53 offset:420
	ds_read_b32 v165, v53 offset:424
	ds_read_b32 v164, v53 offset:428
	ds_read_b32 v187, v53 offset:448
	ds_read_b32 v166, v53 offset:452
	ds_read_b32 v193, v53 offset:456
	ds_read_b32 v192, v53 offset:460
	ds_read_b32 v196, v53 offset:480
	ds_read_b32 v195, v53 offset:484
	ds_read_b32 v204, v53 offset:488
	ds_read_b32 v201, v53 offset:492
	ds_read_b32 v159, v53 offset:384
	s_waitcnt lgkmcnt(0)
	s_nop 4
	v_fmac_f32_e32 v159, 0x3e38aa3b, v0
	s_mov_b64 vcc, s[34:35]
	v_cndmask_b32_e32 v159, v170, v159, vcc
.LBB0_757:
	s_nop 1
	v_fmac_f32_e32 v158, 0x3e38aa3b, v1
	s_mov_b64 vcc, s[34:35]
	v_cndmask_b32_e32 v158, v170, v158, vcc
.LBB0_759:
	v_fmac_f32_e32 v161, 0x3e38aa3b, v2
	s_mov_b64 vcc, s[34:35]
	v_cndmask_b32_e32 v161, v170, v161, vcc
.LBB0_761:
	v_fmac_f32_e32 v160, 0x3e38aa3b, v3
	s_mov_b64 vcc, s[34:35]
	v_cndmask_b32_e32 v160, v170, v160, vcc
.LBB0_763:
	v_fmac_f32_e32 v163, 0x3e38aa3b, v4
	s_mov_b64 vcc, s[34:35]
	v_cndmask_b32_e32 v163, v170, v163, vcc
.LBB0_765:
	v_fmac_f32_e32 v162, 0x3e38aa3b, v5
	s_mov_b64 vcc, s[34:35]
	v_cndmask_b32_e32 v162, v170, v162, vcc
.LBB0_767:
	v_fmac_f32_e32 v165, 0x3e38aa3b, v6
	s_mov_b64 vcc, s[34:35]
	v_cndmask_b32_e32 v165, v170, v165, vcc
.LBB0_769:
	v_fmac_f32_e32 v164, 0x3e38aa3b, v7
	s_mov_b64 vcc, s[34:35]
	v_cndmask_b32_e32 v164, v170, v164, vcc
.LBB0_771:
	v_fmac_f32_e32 v187, 0x3e38aa3b, v8
	s_mov_b64 vcc, s[34:35]
	v_cndmask_b32_e32 v187, v170, v187, vcc
.LBB0_773:
	v_fmac_f32_e32 v166, 0x3e38aa3b, v9
	s_mov_b64 vcc, s[34:35]
	v_cndmask_b32_e32 v166, v170, v166, vcc
.LBB0_775:
	v_fmac_f32_e32 v193, 0x3e38aa3b, v10
	s_mov_b64 vcc, s[34:35]
	v_cndmask_b32_e32 v193, v170, v193, vcc
.LBB0_777:
	v_fmac_f32_e32 v192, 0x3e38aa3b, v11
	s_mov_b64 vcc, s[34:35]
	v_cndmask_b32_e32 v192, v170, v192, vcc
.LBB0_779:
	v_fmac_f32_e32 v196, 0x3e38aa3b, v12
	s_mov_b64 vcc, s[34:35]
	v_cndmask_b32_e32 v196, v170, v196, vcc
.LBB0_781:
	v_fmac_f32_e32 v195, 0x3e38aa3b, v13
	s_mov_b64 vcc, s[34:35]
	v_cndmask_b32_e32 v195, v170, v195, vcc
.LBB0_783:
	v_fmac_f32_e32 v204, 0x3e38aa3b, v14
	s_mov_b64 vcc, s[34:35]
	v_cndmask_b32_e32 v204, v170, v204, vcc
.LBB0_785:
	v_fmac_f32_e32 v201, 0x3e38aa3b, v15
	s_mov_b64 vcc, s[34:35]
	v_cndmask_b32_e32 v201, v170, v201, vcc
.LBB0_787:
	v_add_u32_e32 v152, 4, v78
	v_lshlrev_b32_e32 v78, 5, v152
	v_add_u32_e32 v0, s42, v78
	v_cmp_lt_i32_e32 vcc, -1, v0
	v_cmp_gt_i32_e64 s[36:37], s29, v0
	s_and_b64 s[36:37], vcc, s[36:37]
	v_mov_b32_e32 v0, 0
	v_mov_b32_e32 v1, 0
	v_mov_b32_e32 v2, 0
	v_mov_b32_e32 v3, 0
	v_mov_b32_e32 v4, 0
	v_mov_b32_e32 v5, 0
	v_mov_b32_e32 v6, 0
	v_mov_b32_e32 v7, 0
	v_mov_b32_e32 v8, 0
	v_mov_b32_e32 v9, 0
	v_mov_b32_e32 v10, 0
	v_mov_b32_e32 v11, 0
	v_mov_b32_e32 v12, 0
	v_mov_b32_e32 v13, 0
	v_mov_b32_e32 v14, 0
	v_mov_b32_e32 v15, 0
	s_and_saveexec_b64 s[42:43], s[36:37]
	s_cbranch_execz .LBB0_789
	v_or_b32_e32 v0, v78, v147
	v_mad_u64_u32 v[168:169], s[46:47], v0, s48, v[46:47]
	ds_read_b128 v[0:3], v168
	s_waitcnt lgkmcnt(0)
	v_mfma_f32_32x32x16_bf16 v[0:15], v[0:3], v[66:69], 0
	ds_read_b128 v[66:69], v168 offset:32
	s_waitcnt lgkmcnt(0)
	v_mfma_f32_32x32x16_bf16 v[0:15], v[66:69], v[62:65], v[0:15]
	ds_read_b128 v[62:65], v168 offset:64
	s_waitcnt lgkmcnt(0)
	v_mfma_f32_32x32x16_bf16 v[0:15], v[62:65], v[58:61], v[0:15]
	ds_read_b128 v[58:61], v168 offset:96
	s_waitcnt lgkmcnt(0)
	v_mfma_f32_32x32x16_bf16 v[0:15], v[58:61], v[54:57], v[0:15]
.LBB0_789:
	s_or_b64 exec, exec, s[42:43]
	v_add_u32_e32 v46, 0x80, v71
	s_movk_i32 s29, 0x81
	v_cmp_gt_u32_e32 vcc, s29, v46
	s_and_b64 vcc, s[36:37], vcc
	s_nop 0
	s_nop 0
	s_nop 0
	s_nop 0
	ds_read_b32 v54, v53 offset:512
	s_waitcnt lgkmcnt(0)
	s_nop 0
	v_fmac_f32_e32 v54, 0x3e38aa3b, v0
	v_cndmask_b32_e32 v54, v170, v54, vcc
.LBB0_791:
	s_nop 0
	s_movk_i32 s29, 0xff7e
	v_cmp_lt_u32_e32 vcc, s29, v71
	s_and_b64 vcc, s[36:37], vcc
	s_nop 0
	s_nop 0
	ds_read_b32 v46, v53 offset:516
	s_waitcnt lgkmcnt(0)
	v_fmac_f32_e32 v46, 0x3e38aa3b, v1
	v_cndmask_b32_e32 v46, v170, v46, vcc
.LBB0_793:
	s_nop 0
	v_add_u32_e32 v0, 0x82, v71
	s_movk_i32 s29, 0x81
	v_cmp_gt_u32_e32 vcc, s29, v0
	s_and_b64 vcc, s[36:37], vcc
	s_nop 0
	s_nop 0
	s_nop 0
	ds_read_b32 v1, v53 offset:520
	s_waitcnt lgkmcnt(0)
	v_fmac_f32_e32 v1, 0x3e38aa3b, v2
	v_cndmask_b32_e32 v1, v170, v1, vcc
; #define SHFL_XOR3(v, m, lane) shfl_from((v), (lane) ^ (m))
; DEV void attn_compute(const AttnU& a, const bf16x8 (&qf)[4], int tq, bf16_t* OG, float* LSE, LAS unsigned char* lds, int tid) {
;     ...
; #pragma unroll
;         for (int rg = 0; rg < 16; ++rg) {
;             const int jj = 32 * sb + (rg & 3) + 8 * (rg >> 2) + 4 * hl - n;
;             const bool ok = vb[sb] && ((unsigned)jj <= 128u);
;             const float bia = tab[ok ? jj : 0];
;             const float v = ok ? acc[rg] * SC + bia : -1e30f;
;             acc[rg] = v; mx = fmaxf(mx, v);
;         }
;         s[sb] = acc;
;     }
;     mx = fmaxf(mx, SHFL_XOR3(mx, 32, lane));
.LBB0_795:
	s_nop 0
	v_add_u32_e32 v2, 0x83, v71
	v_cmp_gt_u32_e32 vcc, s29, v2
	s_and_b64 vcc, s[36:37], vcc
	ds_read_b32 v0, v53 offset:524
	s_waitcnt lgkmcnt(0)
	v_fmac_f32_e32 v0, 0x3e38aa3b, v3
	v_cndmask_b32_e32 v0, v170, v0, vcc
.LBB0_797:
	v_add_u32_e32 v2, 0x88, v71
	v_cmp_gt_u32_e32 vcc, s29, v2
	s_and_b64 vcc, s[36:37], vcc
	ds_read_b32 v56, v53 offset:544
	s_waitcnt lgkmcnt(0)
	v_fmac_f32_e32 v56, 0x3e38aa3b, v4
	v_cndmask_b32_e32 v56, v170, v56, vcc
.LBB0_799:
	v_add_u32_e32 v2, 0x89, v71
	v_cmp_gt_u32_e32 vcc, s29, v2
	s_and_b64 vcc, s[36:37], vcc
	ds_read_b32 v55, v53 offset:548
	s_waitcnt lgkmcnt(0)
	v_fmac_f32_e32 v55, 0x3e38aa3b, v5
	v_cndmask_b32_e32 v55, v170, v55, vcc
.LBB0_801:
	v_add_u32_e32 v2, 0x8a, v71
	v_cmp_gt_u32_e32 vcc, s29, v2
	s_and_b64 vcc, s[36:37], vcc
	ds_read_b32 v5, v53 offset:552
	s_waitcnt lgkmcnt(0)
	v_fmac_f32_e32 v5, 0x3e38aa3b, v6
	v_cndmask_b32_e32 v5, v170, v5, vcc
.LBB0_803:
	v_add_u32_e32 v2, 0x8b, v71
	v_cmp_gt_u32_e32 vcc, s29, v2
	s_and_b64 vcc, s[36:37], vcc
	ds_read_b32 v4, v53 offset:556
	s_waitcnt lgkmcnt(0)
	v_fmac_f32_e32 v4, 0x3e38aa3b, v7
	v_cndmask_b32_e32 v4, v170, v4, vcc
.LBB0_805:
	v_add_u32_e32 v2, 0x90, v71
	v_cmp_gt_u32_e32 vcc, s29, v2
	s_and_b64 vcc, s[36:37], vcc
	ds_read_b32 v7, v53 offset:576
	s_waitcnt lgkmcnt(0)
	v_fmac_f32_e32 v7, 0x3e38aa3b, v8
	v_cndmask_b32_e32 v7, v170, v7, vcc
.LBB0_807:
	v_add_u32_e32 v2, 0x91, v71
	v_cmp_gt_u32_e32 vcc, s29, v2
	s_and_b64 vcc, s[36:37], vcc
	ds_read_b32 v6, v53 offset:580
	s_waitcnt lgkmcnt(0)
	v_fmac_f32_e32 v6, 0x3e38aa3b, v9
	v_cndmask_b32_e32 v6, v170, v6, vcc
.LBB0_809:
	v_add_u32_e32 v2, 0x92, v71
	v_cmp_gt_u32_e32 vcc, s29, v2
	s_and_b64 vcc, s[36:37], vcc
	ds_read_b32 v9, v53 offset:584
	s_waitcnt lgkmcnt(0)
	v_fmac_f32_e32 v9, 0x3e38aa3b, v10
	v_cndmask_b32_e32 v9, v170, v9, vcc
.LBB0_811:
	v_add_u32_e32 v2, 0x93, v71
	v_cmp_gt_u32_e32 vcc, s29, v2
	s_and_b64 vcc, s[36:37], vcc
	ds_read_b32 v8, v53 offset:588
	s_waitcnt lgkmcnt(0)
	v_fmac_f32_e32 v8, 0x3e38aa3b, v11
	v_cndmask_b32_e32 v8, v170, v8, vcc
.LBB0_813:
	v_add_u32_e32 v2, 0x98, v71
	v_cmp_gt_u32_e32 vcc, s29, v2
	s_and_b64 vcc, s[36:37], vcc
	ds_read_b32 v11, v53 offset:608
	s_waitcnt lgkmcnt(0)
	v_fmac_f32_e32 v11, 0x3e38aa3b, v12
	v_cndmask_b32_e32 v11, v170, v11, vcc
.LBB0_815:
	v_add_u32_e32 v2, 0x99, v71
	v_cmp_gt_u32_e32 vcc, s29, v2
	s_and_b64 vcc, s[36:37], vcc
	ds_read_b32 v10, v53 offset:612
	s_waitcnt lgkmcnt(0)
	v_fmac_f32_e32 v10, 0x3e38aa3b, v13
	v_cndmask_b32_e32 v10, v170, v10, vcc
.LBB0_817:
	v_add_u32_e32 v2, 0x9a, v71
	v_cmp_gt_u32_e32 vcc, s29, v2
	s_and_b64 vcc, s[36:37], vcc
	ds_read_b32 v58, v53 offset:616
	s_waitcnt lgkmcnt(0)
	v_fmac_f32_e32 v58, 0x3e38aa3b, v14
	v_cndmask_b32_e32 v58, v170, v58, vcc
.LBB0_819:
	v_add_u32_e32 v2, 0x9b, v71
	v_cmp_gt_u32_e32 vcc, s29, v2
	s_and_b64 vcc, s[36:37], vcc
	ds_read_b32 v57, v53 offset:620
	s_waitcnt lgkmcnt(0)
	v_fmac_f32_e32 v57, 0x3e38aa3b, v15
	v_cndmask_b32_e32 v57, v170, v57, vcc
.LBB0_821:
	s_mov_b32 s29, 0xf149f2ca
	v_max3_f32 v3, v49, s29, v48
	v_max3_f32 v3, v3, v51, v50
	v_max3_f32 v3, v3, v70, v52
	v_max3_f32 v3, v3, v73, v72
	v_max3_f32 v3, v3, v75, v74
	v_max3_f32 v3, v3, v77, v76
	v_max3_f32 v3, v3, v80, v79
	v_max3_f32 v3, v3, v82, v81
	v_max3_f32 v3, v3, v84, v83
	v_max3_f32 v3, v3, v86, v85
	v_max3_f32 v3, v3, v88, v87
	v_max3_f32 v3, v3, v90, v89
	v_max3_f32 v3, v3, v92, v91
	v_max3_f32 v3, v3, v94, v93
	v_max3_f32 v3, v3, v96, v95
	v_max3_f32 v3, v3, v98, v97
	v_max3_f32 v3, v3, v100, v99
	v_max3_f32 v3, v3, v102, v101
	v_max3_f32 v3, v3, v104, v103
	v_max3_f32 v3, v3, v106, v105
	v_max3_f32 v3, v3, v108, v107
	v_max3_f32 v3, v3, v153, v109
	v_max3_f32 v3, v3, v155, v154
	v_max3_f32 v3, v3, v157, v156
	v_max3_f32 v3, v3, v159, v158
	v_max3_f32 v3, v3, v161, v160
	v_max3_f32 v3, v3, v163, v162
	v_max3_f32 v3, v3, v165, v164
	v_max3_f32 v3, v3, v187, v166
	v_max3_f32 v3, v3, v193, v192
	v_max3_f32 v3, v3, v196, v195
	v_max3_f32 v3, v3, v204, v201
	v_max3_f32 v3, v3, v54, v46
	v_max3_f32 v3, v3, v1, v0
	v_max3_f32 v3, v3, v56, v55
	v_max3_f32 v3, v3, v5, v4
	v_max3_f32 v3, v3, v7, v6
	v_and_b32_e32 v2, 63, v146
	v_max3_f32 v3, v3, v9, v8
	v_max3_f32 v3, v3, v11, v10
	v_lshlrev_b32_e32 v12, 2, v2
	v_max3_f32 v3, v3, v58, v57
	v_xor_b32_e32 v53, 0x80, v12
	ds_bpermute_b32 v12, v53, v3
	v_mov_b32_e32 v78, 0
	v_mov_b32_e32 v59, 0
	v_mov_b32_e32 v60, 0
	v_mov_b32_e32 v61, 0
	s_waitcnt lgkmcnt(0)
; #define EXP2(x) __builtin_amdgcn_exp2f(x)
; DEV void attn_compute(const AttnU& a, const bf16x8 (&qf)[4], int tq, bf16_t* OG, float* LSE, LAS unsigned char* lds, int tid) {
;     ...
;     float rs = 0.f;
; #pragma unroll
;     for (int sb = 0; sb < 5; ++sb)
; #pragma unroll
;         for (int rg = 0; rg < 16; ++rg) { const float p = EXP2(s[sb][rg] - mx); s[sb][rg] = p; rs += p; }
	v_max_f32_e32 v12, v12, v12
	v_max_f32_e32 v3, v3, v12
	v_sub_f32_e32 v12, v49, v3
	v_exp_f32_e32 v223, v12
	v_sub_f32_e32 v12, v48, v3
	v_exp_f32_e32 v225, v12
	v_sub_f32_e32 v12, v51, v3
	v_exp_f32_e32 v224, v12
	v_sub_f32_e32 v12, v50, v3
	v_exp_f32_e32 v227, v12
	v_sub_f32_e32 v13, v70, v3
	v_add_f32_e32 v12, 0, v223
	v_exp_f32_e32 v226, v13
	v_sub_f32_e32 v13, v52, v3
	v_add_f32_e32 v12, v225, v12
	v_exp_f32_e32 v229, v13
	v_sub_f32_e32 v13, v73, v3
	v_add_f32_e32 v12, v224, v12
	v_exp_f32_e32 v228, v13
	v_sub_f32_e32 v13, v72, v3
	v_add_f32_e32 v12, v227, v12
	v_exp_f32_e32 v230, v13
	v_sub_f32_e32 v13, v75, v3
	v_add_f32_e32 v12, v226, v12
	v_exp_f32_e32 v215, v13
	v_sub_f32_e32 v13, v74, v3
	v_add_f32_e32 v12, v229, v12
	v_exp_f32_e32 v217, v13
	v_sub_f32_e32 v13, v77, v3
	v_add_f32_e32 v12, v228, v12
	v_exp_f32_e32 v216, v13
	v_sub_f32_e32 v13, v76, v3
	v_add_f32_e32 v12, v230, v12
	v_exp_f32_e32 v219, v13
	v_sub_f32_e32 v13, v80, v3
	v_add_f32_e32 v12, v215, v12
	v_exp_f32_e32 v218, v13
	v_sub_f32_e32 v13, v79, v3
	v_add_f32_e32 v12, v217, v12
	v_exp_f32_e32 v221, v13
	v_sub_f32_e32 v13, v82, v3
	v_add_f32_e32 v12, v216, v12
	v_exp_f32_e32 v220, v13
	v_sub_f32_e32 v13, v81, v3
	v_add_f32_e32 v12, v219, v12
	v_exp_f32_e32 v222, v13
	v_sub_f32_e32 v13, v84, v3
	v_add_f32_e32 v12, v218, v12
	v_exp_f32_e32 v208, v13
	v_sub_f32_e32 v13, v83, v3
	v_add_f32_e32 v12, v221, v12
	v_exp_f32_e32 v207, v13
	v_sub_f32_e32 v13, v86, v3
	v_add_f32_e32 v12, v220, v12
	v_exp_f32_e32 v209, v13
	v_sub_f32_e32 v13, v85, v3
	v_add_f32_e32 v12, v222, v12
	v_exp_f32_e32 v211, v13
	v_sub_f32_e32 v13, v88, v3
	v_add_f32_e32 v12, v208, v12
	v_exp_f32_e32 v210, v13
	v_sub_f32_e32 v13, v87, v3
	v_add_f32_e32 v12, v207, v12
	v_exp_f32_e32 v213, v13
	v_sub_f32_e32 v13, v90, v3
	v_add_f32_e32 v12, v209, v12
	v_exp_f32_e32 v212, v13
	v_sub_f32_e32 v13, v89, v3
	v_add_f32_e32 v12, v211, v12
	v_exp_f32_e32 v214, v13
	v_sub_f32_e32 v13, v92, v3
	v_add_f32_e32 v12, v210, v12
	v_exp_f32_e32 v194, v13
	v_sub_f32_e32 v13, v91, v3
	v_add_f32_e32 v12, v213, v12
	v_exp_f32_e32 v198, v13
	v_sub_f32_e32 v13, v94, v3
	v_add_f32_e32 v12, v212, v12
	v_exp_f32_e32 v197, v13
	v_sub_f32_e32 v13, v93, v3
	v_add_f32_e32 v12, v214, v12
	v_exp_f32_e32 v200, v13
	v_sub_f32_e32 v13, v96, v3
	v_add_f32_e32 v12, v194, v12
	v_exp_f32_e32 v199, v13
	v_sub_f32_e32 v13, v95, v3
	v_add_f32_e32 v12, v198, v12
	v_exp_f32_e32 v203, v13
	v_sub_f32_e32 v13, v98, v3
	v_add_f32_e32 v12, v197, v12
	v_exp_f32_e32 v202, v13
	v_sub_f32_e32 v13, v97, v3
	v_add_f32_e32 v12, v200, v12
	v_exp_f32_e32 v205, v13
	v_sub_f32_e32 v13, v100, v3
	v_add_f32_e32 v12, v199, v12
	v_exp_f32_e32 v183, v13
	v_sub_f32_e32 v13, v99, v3
	v_add_f32_e32 v12, v203, v12
	v_exp_f32_e32 v185, v13
	v_sub_f32_e32 v13, v102, v3
	v_add_f32_e32 v12, v202, v12
	v_exp_f32_e32 v184, v13
	v_sub_f32_e32 v13, v101, v3
	v_add_f32_e32 v12, v205, v12
	v_exp_f32_e32 v188, v13
	v_sub_f32_e32 v13, v104, v3
	v_add_f32_e32 v12, v183, v12
	v_exp_f32_e32 v186, v13
	v_sub_f32_e32 v13, v103, v3
	v_add_f32_e32 v12, v185, v12
	v_exp_f32_e32 v190, v13
	v_sub_f32_e32 v13, v106, v3
	v_add_f32_e32 v12, v184, v12
	v_exp_f32_e32 v189, v13
	v_sub_f32_e32 v13, v105, v3
	v_add_f32_e32 v12, v188, v12
	v_exp_f32_e32 v191, v13
	v_sub_f32_e32 v13, v108, v3
	v_add_f32_e32 v12, v186, v12
	v_exp_f32_e32 v175, v13
	v_sub_f32_e32 v13, v107, v3
	v_add_f32_e32 v12, v190, v12
	v_exp_f32_e32 v177, v13
	v_sub_f32_e32 v13, v153, v3
	v_add_f32_e32 v12, v189, v12
	v_exp_f32_e32 v176, v13
	v_sub_f32_e32 v13, v109, v3
	v_add_f32_e32 v12, v191, v12
	v_exp_f32_e32 v179, v13
	v_sub_f32_e32 v13, v155, v3
	v_add_f32_e32 v12, v175, v12
	v_exp_f32_e32 v178, v13
	v_sub_f32_e32 v13, v154, v3
	v_add_f32_e32 v12, v177, v12
	v_exp_f32_e32 v181, v13
	v_sub_f32_e32 v13, v157, v3
	v_add_f32_e32 v12, v176, v12
	v_exp_f32_e32 v180, v13
	v_sub_f32_e32 v13, v156, v3
	v_add_f32_e32 v12, v179, v12
	v_exp_f32_e32 v182, v13
	v_sub_f32_e32 v13, v159, v3
	v_add_f32_e32 v12, v178, v12
	v_exp_f32_e32 v167, v13
	v_sub_f32_e32 v13, v158, v3
	v_add_f32_e32 v12, v181, v12
	v_exp_f32_e32 v169, v13
	v_sub_f32_e32 v13, v161, v3
	v_add_f32_e32 v12, v180, v12
	v_exp_f32_e32 v168, v13
	v_sub_f32_e32 v13, v160, v3
	v_add_f32_e32 v12, v182, v12
	v_exp_f32_e32 v171, v13
	v_sub_f32_e32 v13, v163, v3
	v_add_f32_e32 v12, v167, v12
	v_exp_f32_e32 v170, v13
	v_sub_f32_e32 v13, v162, v3
	v_add_f32_e32 v12, v169, v12
	v_exp_f32_e32 v173, v13
	v_sub_f32_e32 v13, v165, v3
	v_add_f32_e32 v12, v168, v12
	v_exp_f32_e32 v172, v13
	v_sub_f32_e32 v13, v164, v3
	v_add_f32_e32 v12, v171, v12
	v_exp_f32_e32 v174, v13
	v_sub_f32_e32 v13, v187, v3
	v_add_f32_e32 v12, v170, v12
	v_exp_f32_e32 v159, v13
	v_sub_f32_e32 v13, v166, v3
	v_add_f32_e32 v12, v173, v12
	v_exp_f32_e32 v161, v13
	v_sub_f32_e32 v13, v193, v3
	v_add_f32_e32 v12, v172, v12
	v_exp_f32_e32 v160, v13
	v_sub_f32_e32 v13, v192, v3
	v_add_f32_e32 v12, v174, v12
	v_exp_f32_e32 v163, v13
	v_sub_f32_e32 v13, v196, v3
	v_add_f32_e32 v12, v159, v12
	v_exp_f32_e32 v162, v13
	v_sub_f32_e32 v13, v195, v3
	v_add_f32_e32 v12, v161, v12
	v_exp_f32_e32 v165, v13
	v_sub_f32_e32 v13, v204, v3
	v_add_f32_e32 v12, v160, v12
	v_exp_f32_e32 v164, v13
	v_sub_f32_e32 v13, v201, v3
	v_add_f32_e32 v12, v163, v12
	v_exp_f32_e32 v166, v13
	v_add_f32_e32 v12, v162, v12
	v_add_f32_e32 v12, v165, v12
	v_add_f32_e32 v12, v164, v12
	v_add_f32_e32 v15, v166, v12
	v_sub_f32_e32 v12, v54, v3
	v_exp_f32_e32 v12, v12
	v_sub_f32_e32 v13, v46, v3
	v_exp_f32_e32 v14, v13
	v_sub_f32_e32 v1, v1, v3
	v_exp_f32_e32 v13, v1
	v_sub_f32_e32 v0, v0, v3
; #define LAS __attribute__((address_space(3)))
; #define EXP2(x) __builtin_amdgcn_exp2f(x)
; #define SHFL_XOR3(v, m, lane) shfl_from((v), (lane) ^ (m))
; #define MFMA32(a, b, c) __builtin_amdgcn_mfma_f32_32x32x16_bf16((a), (b), (c), 0, 0, 0)
; DEV unsigned pk2(float lo, float hi) { return (unsigned)f2bf(lo) | ((unsigned)f2bf(hi) << 16); }
; DEV void attn_compute(const AttnU& a, const bf16x8 (&qf)[4], int tq, bf16_t* OG, float* LSE, LAS unsigned char* lds, int tid) {
;     ...
;     for (int sb = 0; sb < 5; ++sb)
; #pragma unroll
;         for (int rg = 0; rg < 16; ++rg) { const float p = EXP2(s[sb][rg] - mx); s[sb][rg] = p; rs += p; }
;     rs += SHFL_XOR3(rs, 32, lane);
;     f32x16 oacc[2];
; #pragma unroll
;     for (int eb = 0; eb < 2; ++eb)
; #pragma unroll
;         for (int i = 0; i < 16; ++i) oacc[eb][i] = 0.f;
; #pragma unroll
;     for (int sb = 0; sb < 5; ++sb) {
;         if (!vb[sb]) continue;
; #pragma unroll
;         for (int s2 = 0; s2 < 2; ++s2) {
;             u32x4 w;
;             w.x = pk2(s[sb][8 * s2 + 0], s[sb][8 * s2 + 1]); w.y = pk2(s[sb][8 * s2 + 2], s[sb][8 * s2 + 3]);
;             w.z = pk2(s[sb][8 * s2 + 4], s[sb][8 * s2 + 5]); w.w = pk2(s[sb][8 * s2 + 6], s[sb][8 * s2 + 7]);
;             const bf16x8 pf = BITCAST(bf16x8, w);
; #pragma unroll
;             for (int eb = 0; eb < 2; ++eb) {
;                 const LAS unsigned char* vp = lds + AT_V_OFF + (32 * eb + n) * AT_VP + (32 * (wave + sb) + 16 * s2 + 4 * hl) * 2;
;                 const u32x2 lo = *(const LAS u32x2*)vp, hi = *(const LAS u32x2*)(vp + 16);
;                 u32x4 wv; wv.x = lo.x; wv.y = lo.y; wv.z = hi.x; wv.w = hi.y;
;                 oacc[eb] = MFMA32(BITCAST(bf16x8, wv), pf, oacc[eb]);
;             }
	v_exp_f32_e32 v153, v0
	v_sub_f32_e32 v1, v56, v3
	v_add_f32_e32 v0, v12, v15
	v_exp_f32_e32 v15, v1
	v_sub_f32_e32 v1, v55, v3
	v_add_f32_e32 v0, v14, v0
	v_exp_f32_e32 v155, v1
	v_sub_f32_e32 v1, v5, v3
	v_add_f32_e32 v0, v13, v0
	v_exp_f32_e32 v154, v1
	v_sub_f32_e32 v1, v4, v3
	v_add_f32_e32 v0, v153, v0
	v_exp_f32_e32 v156, v1
	v_sub_f32_e32 v1, v7, v3
	v_add_f32_e32 v0, v15, v0
	v_exp_f32_e32 v4, v1
	v_sub_f32_e32 v1, v6, v3
	v_add_f32_e32 v0, v155, v0
	v_exp_f32_e32 v6, v1
	v_sub_f32_e32 v1, v9, v3
	v_add_f32_e32 v0, v154, v0
	v_exp_f32_e32 v5, v1
	v_sub_f32_e32 v1, v8, v3
	v_add_f32_e32 v0, v156, v0
	v_exp_f32_e32 v8, v1
	v_sub_f32_e32 v1, v11, v3
	v_add_f32_e32 v0, v4, v0
	v_exp_f32_e32 v7, v1
	v_sub_f32_e32 v1, v10, v3
	v_add_f32_e32 v0, v6, v0
	v_exp_f32_e32 v10, v1
	v_sub_f32_e32 v1, v58, v3
	v_add_f32_e32 v0, v5, v0
	v_exp_f32_e32 v9, v1
	v_sub_f32_e32 v1, v57, v3
	v_add_f32_e32 v0, v8, v0
	v_exp_f32_e32 v11, v1
	v_add_f32_e32 v0, v7, v0
	v_add_f32_e32 v0, v10, v0
	v_add_f32_e32 v0, v9, v0
	v_add_f32_e32 v0, v11, v0
	ds_bpermute_b32 v1, v53, v0
	v_lshl_add_u32 v157, v47, 3, 0
	v_mul_u32_u24_e32 v158, 0x308, v147
	v_mov_b32_e32 v79, 0
	v_mov_b32_e32 v80, 0
	v_mov_b32_e32 v81, 0
	v_mov_b32_e32 v82, 0
	v_mov_b32_e32 v83, 0
	v_mov_b32_e32 v84, 0
	v_mov_b32_e32 v85, 0
	v_mov_b32_e32 v86, 0
	v_mov_b32_e32 v87, 0
	v_mov_b32_e32 v88, 0
	v_mov_b32_e32 v89, 0
	v_mov_b32_e32 v90, 0
	v_mov_b32_e32 v91, 0
	v_mov_b32_e32 v92, 0
	v_mov_b32_e32 v93, 0
	v_mov_b32_e32 v94, 0
	v_mov_b32_e32 v95, 0
	v_mov_b32_e32 v96, 0
	v_mov_b32_e32 v97, 0
	v_mov_b32_e32 v98, 0
	v_mov_b32_e32 v99, 0
	v_mov_b32_e32 v100, 0
	v_mov_b32_e32 v101, 0
	v_mov_b32_e32 v102, 0
	v_mov_b32_e32 v103, 0
	v_mov_b32_e32 v104, 0
	v_mov_b32_e32 v105, 0
	v_mov_b32_e32 v106, 0
	v_mov_b32_e32 v107, 0
	v_mov_b32_e32 v108, 0
	v_mov_b32_e32 v109, 0
	v_mov_b32_e32 v46, 0
	v_mov_b32_e32 v47, 0
	v_mov_b32_e32 v48, 0
	v_mov_b32_e32 v49, 0
	v_mov_b32_e32 v50, 0
	v_mov_b32_e32 v51, 0
	v_mov_b32_e32 v52, 0
	v_mov_b32_e32 v53, 0
	v_mov_b32_e32 v54, 0
	v_mov_b32_e32 v55, 0
	v_mov_b32_e32 v56, 0
	v_mov_b32_e32 v57, 0
	v_mov_b32_e32 v58, 0
	v_mov_b32_e32 v62, 0
	v_mov_b32_e32 v63, 0
	v_mov_b32_e32 v64, 0
	v_mov_b32_e32 v65, 0
	v_mov_b32_e32 v66, 0
	v_mov_b32_e32 v67, 0
	v_mov_b32_e32 v68, 0
	v_mov_b32_e32 v69, 0
	v_mov_b32_e32 v70, 0
	v_mov_b32_e32 v71, 0
	v_mov_b32_e32 v72, 0
	v_mov_b32_e32 v73, 0
	v_mov_b32_e32 v74, 0
	v_mov_b32_e32 v75, 0
	v_mov_b32_e32 v76, 0
	v_mov_b32_e32 v77, 0
	s_and_saveexec_b64 s[42:43], s[2:3]
	s_cbranch_execz .LBB0_829
	v_and_b32_e32 v46, 0xffffffc0, v146
	v_bfe_u32 v47, v230, 16, 1
	v_bfe_u32 v48, v229, 16, 1
	v_bfe_u32 v49, v227, 16, 1
	v_add3_u32 v58, v157, v46, v158
	v_add3_u32 v51, v227, v49, s17
	v_add3_u32 v52, v229, v48, s17
	v_add3_u32 v53, v230, v47, s17
	v_bfe_u32 v47, v223, 16, 1
	v_bfe_u32 v48, v224, 16, 1
	v_bfe_u32 v49, v226, 16, 1
	v_add_u32_e32 v59, 0xd800, v58
	v_add3_u32 v55, v226, v49, s17
	v_add3_u32 v56, v224, v48, s17
	v_add3_u32 v57, v223, v47, s17
	ds_read2_b64 v[46:49], v59 offset1:2
	v_bfe_u32 v54, v228, 16, 1
	v_bfe_u32 v50, v225, 16, 1
	v_add3_u32 v54, v228, v54, s17
	v_add3_u32 v50, v225, v50, s17
	v_lshrrev_b32_e32 v57, 16, v57
	v_lshrrev_b32_e32 v56, 16, v56
	v_lshrrev_b32_e32 v55, 16, v55
	v_lshrrev_b32_e32 v54, 16, v54
	s_mov_b32 s2, 0xffff0000
	v_and_or_b32 v53, v53, s2, v54
	v_and_or_b32 v52, v52, s2, v55
	v_and_or_b32 v51, v51, s2, v56
	v_and_or_b32 v50, v50, s2, v57
	s_waitcnt lgkmcnt(0)
	s_nop 0
	v_mfma_f32_32x32x16_bf16 v[78:93], v[46:49], v[50:53], 0
	v_add_u32_e32 v46, 0x6100, v58
	v_add_u32_e32 v58, 0xd800, v46
	ds_read2_b64 v[46:49], v58 offset1:2
	ds_read2_b64 v[54:57], v59 offset0:4 offset1:6
	s_waitcnt lgkmcnt(1)
	v_mfma_f32_32x32x16_bf16 v[94:109], v[46:49], v[50:53], 0
	v_bfe_u32 v48, v219, 16, 1
	v_bfe_u32 v49, v217, 16, 1
	v_add3_u32 v50, v217, v49, s17
	v_add3_u32 v51, v219, v48, s17
	v_bfe_u32 v48, v215, 16, 1
	v_bfe_u32 v49, v216, 16, 1
	v_bfe_u32 v52, v218, 16, 1
	v_bfe_u32 v53, v220, 16, 1
	v_bfe_u32 v46, v222, 16, 1
	v_bfe_u32 v47, v221, 16, 1
	v_add3_u32 v53, v220, v53, s17
	v_add3_u32 v52, v218, v52, s17
	v_add3_u32 v49, v216, v49, s17
	v_add3_u32 v48, v215, v48, s17
	v_add3_u32 v47, v221, v47, s17
	v_add3_u32 v46, v222, v46, s17
	v_lshrrev_b32_e32 v59, 16, v48
	v_lshrrev_b32_e32 v60, 16, v49
	v_lshrrev_b32_e32 v48, 16, v52
	v_lshrrev_b32_e32 v49, 16, v53
	v_and_or_b32 v49, v46, s2, v49
	v_and_or_b32 v48, v47, s2, v48
	v_and_or_b32 v47, v51, s2, v60
	v_and_or_b32 v46, v50, s2, v59
	ds_read2_b64 v[50:53], v58 offset0:4 offset1:6
	s_waitcnt lgkmcnt(1)
	v_mfma_f32_32x32x16_bf16 v[78:93], v[54:57], v[46:49], v[78:93]
	s_waitcnt lgkmcnt(0)
	v_mfma_f32_32x32x16_bf16 v[94:109], v[50:53], v[46:49], v[94:109]
	s_nop 9
	v_mov_b32_e32 v46, v78
	v_mov_b32_e32 v47, v79
	v_mov_b32_e32 v48, v80
	v_mov_b32_e32 v49, v81
	v_mov_b32_e32 v50, v82
	v_mov_b32_e32 v51, v83
	v_mov_b32_e32 v52, v84
	v_mov_b32_e32 v53, v85
	v_mov_b32_e32 v54, v86
	v_mov_b32_e32 v55, v87
	v_mov_b32_e32 v56, v88
	v_mov_b32_e32 v57, v89
	v_mov_b32_e32 v58, v90
	v_mov_b32_e32 v59, v91
	v_mov_b32_e32 v60, v92
	v_mov_b32_e32 v61, v93
	v_mov_b32_e32 v62, v94
	v_mov_b32_e32 v63, v95
	v_mov_b32_e32 v64, v96
	v_mov_b32_e32 v65, v97
	v_mov_b32_e32 v66, v98
	v_mov_b32_e32 v67, v99
	v_mov_b32_e32 v68, v100
	v_mov_b32_e32 v69, v101
	v_mov_b32_e32 v70, v102
	v_mov_b32_e32 v71, v103
	v_mov_b32_e32 v72, v104
	v_mov_b32_e32 v73, v105
	v_mov_b32_e32 v74, v106
	v_mov_b32_e32 v75, v107
	v_mov_b32_e32 v76, v108
	v_mov_b32_e32 v77, v109
	s_or_b64 exec, exec, s[42:43]
	s_and_saveexec_b64 s[2:3], s[6:7]
	s_cbranch_execnz .LBB0_830
